# stagger GEMM phase start per XCD group ((block&7)*3us) for multi-unit GEMM phases to de-synchronise epilogue store bursts
# speedup vs baseline: 1.0482x; 1.0482x over previous
; #define PG8_STAGE(bufoff, gbase, voff) do { _Pragma("unroll") for (int _i = 0; _i < 2; ++_i) \
;         __builtin_amdgcn_global_load_lds((const unsigned*)((const char*)(gbase) + (voff)[_i]), (PG8_LAS unsigned*)(lds + (bufoff) + ldsw + _i * 8192), 16, 0, 0); } while (0)
; #define PG8_WAIT_V(n) asm volatile("s_waitcnt vmcnt(" #n ")" ::: "memory")
; #define PG8_BAR __builtin_amdgcn_s_barrier()
; template <class Epi, class Sched, bool ALIGN_EPI = false, bool SP2 = false>
; __device__ __forceinline__ void gemm_phase(PG8_LAS unsigned char* lds, const Gemm g, const Sched& S, const Epi& E) {
;     const int tid = threadIdx.x, wid = __builtin_amdgcn_readfirstlane(tid >> 6), lane = tid & 63, wr = wid >> 2, wc = wid & 3, fr = lane & 15, fq = lane >> 4;
;     const int K = g.K, nt = K / BK;
;     unsigned voffA[2], voffB[2];
; #pragma unroll
;     for (int i = 0; i < 2; ++i) { int R, C; stage_rc(tid * 16 + i * 8192, R, C); const int Rb = Epi::PERM ? ((R & ~31) + perm32(R & 31)) : R;
;         voffA[i] = (unsigned)(R * K + C) * 2u; voffB[i] = (unsigned)(Rb * K + C) * 2u; }
;     const size_t kstep = (size_t)(BK * 2);
;     const size_t hstep = (size_t)HALF * K * 2;
;     const size_t tstep = 2 * hstep;
;     const unsigned ldsw = (unsigned)wid * 1024u;
;     const int aoff = lds_byte(wr * 64 + fr, fq * 8), boff = lds_byte(wc * 32 + fr, fq * 8);
;     ...
;     Unit cur, nxt; int ui = 0;
;     if (!S.next(0, cur)) return;
;     f32x4 acc[2][2][4][2];
; #pragma unroll
;     for (int a = 0; a < 2; ++a)
; #pragma unroll
;         for (int b = 0; b < 2; ++b)
; #pragma unroll
;             for (int m = 0; m < 4; ++m)
; #pragma unroll
;                 for (int n = 0; n < 2; ++n) acc[a][b][m][n] = (f32x4){0.f, 0.f, 0.f, 0.f};
;     bf16x8 At[4][2], B0[2][2], B1[2][2];
;     const char* cA = (const char*)g.A + (size_t)cur.pm * tstep; const char* cB = (const char*)g.Bt + (size_t)cur.pn * tstep;
;     S.a_ready(cur);
;     if constexpr (SP2) {
;         PG8_STAGE(PG8_SB(0, 0), cB, voffB); PG8_STAGE(PG8_SB(0, 1), cB + hstep, voffB); PG8_STAGE(PG8_SA(0, 0), cA, voffA); PG8_STAGE(PG8_SA(0, 1), cA + hstep, voffA);
;         if (wr == 1) PG8_BAR;
;         PG8_WAIT_V(2); PG8_BAR;
.LBB0_39:
	s_andn2_b64 vcc, exec, s[14:15]
	v_writelane_b32 v253, s27, 27
	s_cbranch_vccnz .LBB0_80
	s_lshl_b32 s90, s20, 5
	s_cmp_lt_i32 s68, s90
	v_readfirstlane_b32 s23, v210
	s_cbranch_scc0 .LBB0_80
	s_cmp_lt_u32 s20, 9
	s_cbranch_scc1 .Lstg_skip
	s_and_b32 s28, s68, 7
	s_mul_i32 s28, s28, 300
	s_lshr_b32 s29, s68, 3
	s_mul_i32 s29, s29, 0
	s_add_u32 s28, s28, s29
	s_memrealtime s[24:25]
	s_waitcnt lgkmcnt(0)
.Lstg_loop:
	s_memrealtime s[26:27]
	s_waitcnt lgkmcnt(0)
	s_sub_u32 s29, s26, s24
	s_cmp_lt_u32 s29, s28
	s_cbranch_scc1 .Lstg_loop
.Lstg_skip:
	v_mul_u32_u24_e32 v0, s22, v252
	v_or_b32_e32 v2, v0, v211
	v_lshlrev_b32_e32 v190, 1, v2
	v_mul_u32_u24_e32 v2, s22, v234
	v_or_b32_e32 v2, v2, v211
	v_mul_u32_u24_e32 v14, s22, v214
	v_lshlrev_b32_e32 v192, 1, v2
	v_or_b32_e32 v2, v14, v211
	v_lshlrev_b32_e32 v194, 1, v2
	v_mul_u32_u24_e32 v2, s22, v215
	v_or_b32_e32 v2, v2, v211
	s_lshl_b32 s40, s20, 3
	v_lshlrev_b32_e32 v196, 1, v2
	v_cvt_f32_u32_e32 v2, s40
	v_writelane_b32 v253, s30, 35
	s_lshl_b32 s39, s20, 2
	s_sub_i32 s25, 0, s40
	v_rcp_iflag_f32_e32 v2, v2
	v_writelane_b32 v253, s31, 36
	s_xor_b64 s[14:15], s[4:5], -1
	v_readlane_b32 s20, v253, 8
	v_mul_f32_e32 v2, 0x4f7ffffe, v2
	v_cvt_u32_f32_e32 v2, v2
	s_or_b32 s20, s39, s20
	v_readlane_b32 s21, v253, 7
	s_mul_i32 s20, s20, s21
	v_readfirstlane_b32 s42, v2
	v_readlane_b32 s21, v253, 4
	s_mul_i32 s25, s25, s42
	s_add_i32 s20, s20, s21
	s_mul_hi_u32 s25, s42, s25
	s_abs_i32 s24, s20
	s_add_i32 s42, s42, s25
	s_mul_hi_u32 s25, s24, s42
	s_mul_i32 s26, s25, s40
	s_lshl_b32 s16, s22, 8
	s_mov_b32 s17, s91
	s_lshr_b32 s4, s23, 6
	s_sub_i32 s24, s24, s26
	s_lshl_b64 s[18:19], s[16:17], 1
	s_lshr_b32 s5, s23, 8
	s_lshl_b32 s41, s4, 10
	s_ashr_i32 s21, s20, 31
	s_add_i32 s26, s25, 1
	s_sub_i32 s27, s24, s40
	s_cmp_ge_u32 s24, s40
	s_cselect_b32 s25, s26, s25
	s_cselect_b32 s24, s27, s24
	s_add_i32 s26, s25, 1
	s_cmp_ge_u32 s24, s40
	s_cselect_b32 s24, s26, s25
	s_xor_b32 s24, s24, s21
	s_sub_i32 s21, s24, s21
	s_lshl_b32 s24, s21, 3
	s_sub_i32 s25, 32, s24
	s_min_i32 s25, s25, 8
	s_abs_i32 s27, s25
	v_cvt_f32_u32_e32 v2, s27
	s_sub_i32 s28, 0, s27
	s_mul_i32 s21, s21, s40
	s_sub_i32 s20, s20, s21
	v_rcp_iflag_f32_e32 v2, v2
	s_abs_i32 s26, s20
	s_xor_b32 s21, s20, s25
	s_ashr_i32 s21, s21, 31
	v_mul_f32_e32 v2, 0x4f7ffffe, v2
	v_cvt_u32_f32_e32 v2, v2
	v_mov_b32_e32 v193, v1
	v_mov_b32_e32 v197, v1
	v_mov_b32_e32 v191, v1
	v_readfirstlane_b32 s29, v2
	s_mul_i32 s28, s28, s29
	s_mul_hi_u32 s28, s29, s28
	s_add_i32 s29, s29, s28
	s_mul_hi_u32 s28, s26, s29
	s_mul_i32 s29, s28, s27
	s_sub_i32 s26, s26, s29
	s_add_i32 s29, s28, 1
	s_sub_i32 s30, s26, s27
	s_cmp_ge_u32 s26, s27
	s_cselect_b32 s28, s29, s28
	s_cselect_b32 s26, s30, s26
	s_add_i32 s29, s28, 1
	s_cmp_ge_u32 s26, s27
	s_cselect_b32 s26, s29, s28
	s_xor_b32 s26, s26, s21
	s_sub_i32 s53, s26, s21
	s_mul_i32 s21, s53, s25
	s_sub_i32 s20, s20, s21
	s_add_i32 s54, s20, s24
	s_ashr_i32 s20, s54, 31
	s_mul_i32 s20, s18, s20
	s_mul_hi_u32 s21, s18, s54
	s_add_i32 s20, s21, s20
	s_bfe_u32 s21, s22, 0x10017
	s_mul_i32 s24, s21, s54
	s_add_i32 s24, s20, s24
	s_ashr_i32 s20, s53, 31
	s_mul_i32 s20, s18, s20
	s_mul_hi_u32 s26, s18, s53
	s_add_i32 s20, s26, s20
	s_mul_i32 s21, s21, s53
	s_add_i32 s20, s20, s21
	s_mul_i32 s21, s18, s53
	s_add_u32 s30, s8, s21
	s_addc_u32 s31, s9, s20
	s_add_i32 s43, s41, 0
	s_add_i32 m0, s43, 0x10000
	s_mul_i32 s25, s18, s54
	global_load_lds_dwordx4 v192, s[30:31]
	s_add_i32 m0, s43, 0x12000
	s_add_u32 s20, s30, s16
	global_load_lds_dwordx4 v196, s[30:31]
	s_addc_u32 s21, s31, 0
	s_add_i32 m0, s43, 0x14000
	v_lshl_add_u64 v[6:7], s[20:21], 0, v[192:193]
	global_load_lds_dwordx4 v192, s[20:21]
	s_add_i32 m0, s43, 0x16000
	s_add_u32 s28, s12, s25
	s_addc_u32 s29, s13, s24
	s_add_i32 s44, s43, 0x2000
	v_lshl_add_u64 v[8:9], s[20:21], 0, v[196:197]
	global_load_lds_dwordx4 v196, s[20:21]
	s_mov_b32 m0, s43
	s_add_u32 s20, s28, s16
	global_load_lds_dwordx4 v190, s[28:29]
	s_mov_b32 m0, s44
	s_addc_u32 s21, s29, 0
	s_add_i32 s45, s43, 0x4000
	global_load_lds_dwordx4 v194, s[28:29]
	s_mov_b32 m0, s45
	s_add_i32 s46, s43, 0x6000
	global_load_lds_dwordx4 v190, s[20:21]
	s_mov_b32 m0, s46
	v_mov_b32_e32 v195, v1
	global_load_lds_dwordx4 v194, s[20:21]
	s_cmp_eq_u32 s5, 1
	v_lshl_add_u64 v[2:3], s[30:31], 0, v[192:193]
	v_lshl_add_u64 v[4:5], s[30:31], 0, v[196:197]
	v_lshl_add_u64 v[10:11], s[28:29], 0, v[190:191]
	v_lshl_add_u64 v[12:13], s[28:29], 0, v[194:195]
	s_cselect_b64 s[20:21], -1, 0
	s_cmp_lg_u32 s5, 1
	s_cbranch_scc1 .LBB0_43
	s_barrier
